# static priority raise (s_setprio 2) for waves 4-7 during the chunk QK section (longest causal chains), back to 0 before the C0 slice loop
# baseline (speedup 1.0000x reference)
.LBB0_1252:
	s_or_b64 exec, exec, s[56:57]
	v_readfirstlane_b32 s99, v179
	s_cmp_lt_u32 s99, 4
	s_cbranch_scc1 .Lqk_noprio
	s_setprio 2
.Lqk_noprio:
	s_lshl_b32 s14, s65, 1
	v_lshl_add_u64 v[2:3], v[66:67], 0, s[14:15]
	v_or_b32_e32 v0, s38, v60
	v_mad_u64_u32 v[56:57], s[56:57], v0, s63, v[2:3]
	s_mul_i32 s14, s39, 0x600
	v_add_u32_e32 v91, v73, v62
	v_add_u32_e32 v57, s14, v57
	s_waitcnt lgkmcnt(0)
	s_barrier
	ds_read_b128 v[32:35], v71
	ds_read_b128 v[28:31], v71 offset:64
	ds_read_b128 v[24:27], v71 offset:128
	ds_read_b128 v[20:23], v71 offset:192
	ds_read_b128 v[16:19], v71 offset:256
	ds_read_b128 v[12:15], v71 offset:320
	ds_read_b128 v[8:11], v91 offset:51712
	flat_load_dwordx4 v[36:39], v[56:57]
	flat_load_dwordx4 v[40:43], v[56:57] offset:64
	flat_load_dwordx4 v[44:47], v[56:57] offset:128
	flat_load_dwordx4 v[48:51], v[56:57] offset:192
	flat_load_dwordx4 v[52:55], v[56:57] offset:256
	s_nop 0
	flat_load_dwordx4 v[56:59], v[56:57] offset:320
	ds_read_b32 v0, v75 offset:51200
	s_waitcnt vmcnt(0) lgkmcnt(0)
	v_mfma_f32_16x16x32_bf16 v[36:39], v[32:35], v[36:39], 0
	v_mfma_f32_16x16x32_bf16 v[36:39], v[28:31], v[40:43], v[36:39]
	v_sub_f32_e32 v40, v0, v8
	v_mul_f32_e32 v40, 0x3fb8aa3b, v40
	v_exp_f32_e32 v40, v40
	v_mfma_f32_16x16x32_bf16 v[36:39], v[24:27], v[44:47], v[36:39]
	v_mov_b32_e32 v41, 0
	v_mfma_f32_16x16x32_bf16 v[36:39], v[20:23], v[48:51], v[36:39]
	v_mfma_f32_16x16x32_bf16 v[36:39], v[16:19], v[52:55], v[36:39]
	v_mfma_f32_16x16x32_bf16 v[36:39], v[12:15], v[56:59], v[36:39]
	s_nop 7
	v_mul_f32_e32 v36, v36, v40
	v_cndmask_b32_e64 v36, v36, 0, s[22:23]
	v_bfe_u32 v40, v36, 16, 1
	v_add3_u32 v36, v36, v40, s64
	ds_write_b16_d16_hi v101, v36 offset:55808
	v_sub_f32_e32 v36, v0, v9
	v_mul_f32_e32 v36, 0x3fb8aa3b, v36
	v_exp_f32_e32 v36, v36
	v_mov_b32_e32 v40, 0
	v_mul_f32_e32 v36, v37, v36
	v_cndmask_b32_e64 v36, v36, 0, s[24:25]
	v_bfe_u32 v37, v36, 16, 1
	v_add3_u32 v36, v36, v37, s64
	ds_write_b16_d16_hi v101, v36 offset:56080
	v_sub_f32_e32 v36, v0, v10
	v_mul_f32_e32 v36, 0x3fb8aa3b, v36
	v_exp_f32_e32 v36, v36
	v_sub_f32_e32 v0, v0, v11
	v_mul_f32_e32 v0, 0x3fb8aa3b, v0
	v_exp_f32_e32 v0, v0
	v_mul_f32_e32 v36, v38, v36
	v_cndmask_b32_e64 v36, v36, 0, s[26:27]
	v_bfe_u32 v37, v36, 16, 1
	v_mul_f32_e32 v0, v39, v0
	v_add3_u32 v36, v36, v37, s64
	v_cndmask_b32_e64 v0, v0, 0, s[28:29]
	ds_write_b16_d16_hi v101, v36 offset:56352
	v_bfe_u32 v36, v0, 16, 1
	v_add3_u32 v0, v0, v36, s64
	v_mov_b32_e32 v36, 0
	v_mov_b32_e32 v38, 0
	v_mov_b32_e32 v39, 0
	ds_write_b16_d16_hi v101, v0 offset:56624
	s_and_saveexec_b64 s[56:57], s[30:31]
	s_cbranch_execz .LBB0_1254
	v_or_b32_e32 v0, s38, v68
	v_mad_u64_u32 v[46:47], s[58:59], v0, s63, v[2:3]
	v_add_u32_e32 v47, s14, v47
	global_load_dwordx4 v[38:41], v[46:47], off
	global_load_dwordx4 v[42:45], v[46:47], off offset:64
	global_load_dwordx4 v[148:151], v[46:47], off offset:128
	global_load_dwordx4 v[152:155], v[46:47], off offset:192
	global_load_dwordx4 v[156:159], v[46:47], off offset:256
	global_load_dwordx4 v[160:163], v[46:47], off offset:320
	s_waitcnt vmcnt(0) lgkmcnt(0)
	v_mfma_f32_16x16x32_bf16 v[38:41], v[32:35], v[38:41], 0
	v_mfma_f32_16x16x32_bf16 v[38:41], v[28:31], v[42:45], v[38:41]
	v_mfma_f32_16x16x32_bf16 v[38:41], v[24:27], v[148:151], v[38:41]
	v_mfma_f32_16x16x32_bf16 v[38:41], v[20:23], v[152:155], v[38:41]
	v_mfma_f32_16x16x32_bf16 v[38:41], v[16:19], v[156:159], v[38:41]
	v_mfma_f32_16x16x32_bf16 v[38:41], v[12:15], v[160:163], v[38:41]

.Lc0_noscl:
	s_setprio 0
